# scan phase waits on a per-(batch,head) counter (32 arrivals) instead of the global 256-arrival counter
# speedup vs baseline: 1.0018x; 1.0018x over previous
; #define GSYNC() do { xcd_barrier(xbar); xcd_barrier(xbar); } while (0)
; #define GSYNC() xcd_barrier(xbar)
; #define REP(p) for (int rep_ = 0; rep_ < (((PROBE_MASK >> (p)) & 1) ? 2 : 1); ++rep_)
; __global__ void __launch_bounds__(NTHR, 2) fwd_megakernel(Args args) {
;     ...
;     weight_copy_items(args, lds, 16 * 96 + 32, 16 * 96 + 32 + 16 * 32 + 16 * 129 + 16 * 32, G);
;     GSYNC(); }
;     REP(4) { hgrn_scan_phase((const float*)(ws + WS_LST), (const float*)(ws + WS_DTOT), (float*)(ws + WS_SST), G);
.Lp3_cnt_done:
	v_mov_b32_e32 v250, 0
	v_mov_b32_e32 v251, s98
	s_cmp_eq_u32 s6, 0x100
	s_cbranch_scc0 .Lp3_glob
	s_lshr_b32 s99, s91, 5
	s_lshl_b32 s99, s99, 8
	s_add_i32 s99, s99, 0x1800
	v_mov_b32_e32 v250, s99
	global_atomic_add v250, v251, s[10:11]
	s_branch .Lp3_sig_done
.Lp3_glob:
	global_atomic_add v250, v251, s[10:11] offset:3328

; #define GSYNC() do { xcd_barrier(xbar); xcd_barrier(xbar); } while (0)
; #define GSYNC() xcd_barrier(xbar)
; #define REP(p) for (int rep_ = 0; rep_ < (((PROBE_MASK >> (p)) & 1) ? 2 : 1); ++rep_)
; __global__ void __launch_bounds__(NTHR, 2) fwd_megakernel(Args args) {
;     ...
;     GSYNC(); }
;     REP(4) { hgrn_scan_phase((const float*)(ws + WS_LST), (const float*)(ws + WS_DTOT), (float*)(ws + WS_SST), G);
.LBB0_346:
	s_or_b64 exec, exec, s[0:1]
	s_waitcnt vmcnt(0)
	s_and_saveexec_b64 s[100:101], s[92:93]
	s_cbranch_execz .Lp4_polled
	s_cmp_eq_u32 s6, 0x100
	s_cbranch_scc0 .Lp4_glob
	s_lshr_b32 s98, s91, 5
	s_lshl_b32 s98, s98, 8
	s_add_i32 s98, s98, 0x1800
	v_mov_b32_e32 v250, s98
.Lp4_gpoll:
	global_load_dword v251, v250, s[10:11] sc1
	s_waitcnt vmcnt(0)
	v_cmp_gt_u32_e32 vcc, 32, v251
	s_nop 1
	s_cbranch_vccz .Lp4_pollend
	s_sleep 1
	s_branch .Lp4_gpoll
.Lp4_glob:
	v_mov_b32_e32 v250, 0
.Lp4_poll:
	global_load_dword v251, v250, s[10:11] offset:3328 sc1
	s_waitcnt vmcnt(0)
	v_cmp_gt_u32_e32 vcc, 0x100, v251
	s_nop 1
	s_cbranch_vccz .Lp4_pollend
	s_sleep 1
	s_branch .Lp4_poll
